# K-loop: A-fragment LDS reads rebalanced 6/6 across phases via two spare fragment quads (on top of SALU trim + EpiIn fast path)
# speedup vs baseline: 1.0122x; 1.0002x over previous
.LBB0_385:
	s_add_i32 s43, s6, -2
	s_add_u32 s0, s46, 0x80
	s_addc_u32 s1, s47, 0
	s_add_u32 s48, s44, 0x100
	v_mov_b32_e32 v2, 0
	s_addc_u32 s49, s45, 0
	s_mov_b32 s44, 0
	v_mov_b32_e32 v3, v2
	v_mov_b32_e32 v4, v2
	v_mov_b32_e32 v5, v2
	v_mov_b32_e32 v6, v2
	v_mov_b32_e32 v7, v2
	v_mov_b32_e32 v8, v2
	v_mov_b32_e32 v9, v2
	s_waitcnt vmcnt(0)
	v_mov_b32_e32 v18, v2
	v_mov_b32_e32 v19, v2
	v_mov_b32_e32 v20, v2
	v_mov_b32_e32 v21, v2
	v_mov_b32_e32 v22, v2
	v_mov_b32_e32 v23, v2
	v_mov_b32_e32 v24, v2
	v_mov_b32_e32 v25, v2
	v_mov_b32_e32 v34, v2
	v_mov_b32_e32 v35, v2
	v_mov_b32_e32 v36, v2
	v_mov_b32_e32 v37, v2
	v_mov_b32_e32 v38, v2
	v_mov_b32_e32 v39, v2
	v_mov_b32_e32 v40, v2
	v_mov_b32_e32 v41, v2
	v_mov_b32_e32 v50, v2
	v_mov_b32_e32 v51, v2
	v_mov_b32_e32 v52, v2
	v_mov_b32_e32 v53, v2
	v_mov_b32_e32 v54, v2
	v_mov_b32_e32 v55, v2
	v_mov_b32_e32 v56, v2
	v_mov_b32_e32 v57, v2
	v_mov_b32_e32 v10, v2
	v_mov_b32_e32 v11, v2
	v_mov_b32_e32 v12, v2
	v_mov_b32_e32 v13, v2
	v_mov_b32_e32 v14, v2
	v_mov_b32_e32 v15, v2
	v_mov_b32_e32 v16, v2
	v_mov_b32_e32 v17, v2
	v_mov_b32_e32 v26, v2
	v_mov_b32_e32 v27, v2
	v_mov_b32_e32 v28, v2
	v_mov_b32_e32 v29, v2
	v_mov_b32_e32 v30, v2
	v_mov_b32_e32 v31, v2
	v_mov_b32_e32 v32, v2
	v_mov_b32_e32 v33, v2
	v_mov_b32_e32 v42, v2
	v_mov_b32_e32 v43, v2
	v_mov_b32_e32 v44, v2
	v_mov_b32_e32 v45, v2
	v_mov_b32_e32 v46, v2
	v_mov_b32_e32 v47, v2
	v_mov_b32_e32 v48, v2
	v_mov_b32_e32 v49, v2
	v_mov_b32_e32 v58, v2
	v_mov_b32_e32 v59, v2
	v_mov_b32_e32 v60, v2
	v_mov_b32_e32 v61, v2
	v_mov_b32_e32 v62, v2
	v_mov_b32_e32 v63, v2
	v_mov_b32_e32 v64, v2
	v_mov_b32_e32 v65, v2
	v_mov_b32_e32 v66, v2
	v_mov_b32_e32 v67, v2
	v_mov_b32_e32 v68, v2
	v_mov_b32_e32 v69, v2
	v_mov_b32_e32 v70, v2
	v_mov_b32_e32 v71, v2
	v_mov_b32_e32 v72, v2
	v_mov_b32_e32 v73, v2
	v_mov_b32_e32 v82, v2
	v_mov_b32_e32 v83, v2
	s_waitcnt vmcnt(0)
	v_mov_b32_e32 v84, v2
	v_mov_b32_e32 v85, v2
	v_mov_b32_e32 v86, v2
	v_mov_b32_e32 v87, v2
	v_mov_b32_e32 v88, v2
	v_mov_b32_e32 v89, v2
	v_mov_b32_e32 v98, v2
	v_mov_b32_e32 v99, v2
	v_mov_b32_e32 v100, v2
	v_mov_b32_e32 v101, v2
	v_mov_b32_e32 v102, v2
	v_mov_b32_e32 v103, v2
	v_mov_b32_e32 v104, v2
	v_mov_b32_e32 v105, v2
	v_mov_b32_e32 v114, v2
	v_mov_b32_e32 v115, v2
	v_mov_b32_e32 v116, v2
	v_mov_b32_e32 v117, v2
	v_mov_b32_e32 v118, v2
	v_mov_b32_e32 v119, v2
	v_mov_b32_e32 v120, v2
	v_mov_b32_e32 v121, v2
	v_mov_b32_e32 v74, v2
	v_mov_b32_e32 v75, v2
	v_mov_b32_e32 v76, v2
	v_mov_b32_e32 v77, v2
	v_mov_b32_e32 v78, v2
	v_mov_b32_e32 v79, v2
	v_mov_b32_e32 v80, v2
	v_mov_b32_e32 v81, v2
	v_mov_b32_e32 v90, v2
	v_mov_b32_e32 v91, v2
	v_mov_b32_e32 v92, v2
	v_mov_b32_e32 v93, v2
	v_mov_b32_e32 v94, v2
	v_mov_b32_e32 v95, v2
	v_mov_b32_e32 v96, v2
	v_mov_b32_e32 v97, v2
	v_mov_b32_e32 v106, v2
	v_mov_b32_e32 v107, v2
	v_mov_b32_e32 v108, v2
	v_mov_b32_e32 v109, v2
	v_mov_b32_e32 v110, v2
	v_mov_b32_e32 v111, v2
	v_mov_b32_e32 v112, v2
	v_mov_b32_e32 v113, v2
	v_mov_b32_e32 v122, v2
	v_mov_b32_e32 v123, v2
	v_mov_b32_e32 v124, v2
	v_mov_b32_e32 v125, v2
	v_mov_b32_e32 v126, v2
	v_mov_b32_e32 v127, v2
	v_mov_b32_e32 v128, v2
	v_mov_b32_e32 v129, v2
	s_waitcnt lgkmcnt(0)
	s_add_i32 s71, s44, 2
	s_add_u32 s46, s0, 0x80
	s_addc_u32 s45, s1, 0
	s_cmp_eq_u32 s43, s44
	s_cselect_b32 s44, s72, s46
	s_cselect_b32 s45, s73, s45
	s_cselect_b32 s47, s75, s49
	s_cselect_b32 s46, s74, s48
	v_add_u32_e32 v0, 0x10000, v224
	ds_read_b128 v[130:133], v0
	ds_read_b128 v[134:137], v0 offset:1024
	ds_read_b128 v[138:141], v0 offset:2048
	ds_read_b128 v[142:145], v0 offset:3072
	ds_read_b128 v[146:149], v229
	ds_read_b128 v[150:153], v229 offset:1024
.LBB0_386:
	s_add_i32 m0, s98, 0xc000
	ds_read_b128 v[176:179], v229 offset:2048
	ds_read_b128 v[180:183], v229 offset:3072
	ds_read_b128 v[184:187], v229 offset:4096
	ds_read_b128 v[188:191], v229 offset:5120
	ds_read_b128 v[192:195], v229 offset:6144
	ds_read_b128 v[196:199], v229 offset:7168
	global_load_lds_dwordx4 v172, s[0:1]
	s_add_i32 m0, s98, 0xe000
	s_nop 0
	global_load_lds_dwordx4 v174, s[0:1]
	s_waitcnt lgkmcnt(6)
	s_barrier
	s_waitcnt lgkmcnt(0)
	v_mfma_f32_16x16x32_bf16 v[126:129], v[130:133], v[146:149], v[126:129]
	v_mfma_f32_16x16x32_bf16 v[122:125], v[138:141], v[146:149], v[122:125]
	v_mfma_f32_16x16x32_bf16 v[110:113], v[130:133], v[176:179], v[110:113]
	v_mfma_f32_16x16x32_bf16 v[106:109], v[138:141], v[176:179], v[106:109]
	v_mfma_f32_16x16x32_bf16 v[94:97], v[130:133], v[184:187], v[94:97]
	v_mfma_f32_16x16x32_bf16 v[90:93], v[138:141], v[184:187], v[90:93]
	v_mfma_f32_16x16x32_bf16 v[78:81], v[130:133], v[192:195], v[78:81]
	v_mfma_f32_16x16x32_bf16 v[74:77], v[138:141], v[192:195], v[74:77]
	v_mfma_f32_16x16x32_bf16 v[126:129], v[134:137], v[150:153], v[126:129]
	v_mfma_f32_16x16x32_bf16 v[122:125], v[142:145], v[150:153], v[122:125]
	v_mfma_f32_16x16x32_bf16 v[110:113], v[134:137], v[180:183], v[110:113]
	v_mfma_f32_16x16x32_bf16 v[106:109], v[142:145], v[180:183], v[106:109]
	v_mfma_f32_16x16x32_bf16 v[94:97], v[134:137], v[188:191], v[94:97]
	v_mfma_f32_16x16x32_bf16 v[90:93], v[142:145], v[188:191], v[90:93]
	v_mfma_f32_16x16x32_bf16 v[78:81], v[134:137], v[196:199], v[78:81]
	v_mfma_f32_16x16x32_bf16 v[74:77], v[142:145], v[196:199], v[74:77]
	s_barrier
	v_add_u32_e32 v0, 0x14000, v224
	s_add_i32 vcc_lo, s97, 0x10000
	s_mov_b32 m0, vcc_lo
	ds_read_b128 v[200:203], v0
	ds_read_b128 v[230:233], v0 offset:1024
	ds_read_b128 v[234:237], v0 offset:2048
	ds_read_b128 v[238:241], v0 offset:3072
	ds_read_b128 v[242:245], v229 offset:16384
	ds_read_b128 v[246:249], v229 offset:17408
	global_load_lds_dwordx4 v158, s[46:47]
	s_add_i32 m0, vcc_lo, 0x2000
	s_nop 0
	global_load_lds_dwordx4 v162, s[46:47]
	s_waitcnt vmcnt(6)
	s_barrier
	s_waitcnt lgkmcnt(0)
	v_mfma_f32_16x16x32_bf16 v[118:121], v[200:203], v[146:149], v[118:121]
	v_mfma_f32_16x16x32_bf16 v[114:117], v[234:237], v[146:149], v[114:117]
	v_mfma_f32_16x16x32_bf16 v[102:105], v[200:203], v[176:179], v[102:105]
	v_mfma_f32_16x16x32_bf16 v[98:101], v[234:237], v[176:179], v[98:101]
	v_mfma_f32_16x16x32_bf16 v[86:89], v[200:203], v[184:187], v[86:89]
	v_mfma_f32_16x16x32_bf16 v[82:85], v[234:237], v[184:187], v[82:85]
	v_mfma_f32_16x16x32_bf16 v[70:73], v[200:203], v[192:195], v[70:73]
	v_mfma_f32_16x16x32_bf16 v[66:69], v[234:237], v[192:195], v[66:69]
	v_mfma_f32_16x16x32_bf16 v[118:121], v[230:233], v[150:153], v[118:121]
	v_mfma_f32_16x16x32_bf16 v[114:117], v[238:241], v[150:153], v[114:117]
	v_mfma_f32_16x16x32_bf16 v[102:105], v[230:233], v[180:183], v[102:105]
	v_mfma_f32_16x16x32_bf16 v[98:101], v[238:241], v[180:183], v[98:101]
	v_mfma_f32_16x16x32_bf16 v[86:89], v[230:233], v[188:191], v[86:89]
	v_mfma_f32_16x16x32_bf16 v[82:85], v[238:241], v[188:191], v[82:85]
	v_mfma_f32_16x16x32_bf16 v[70:73], v[230:233], v[196:199], v[70:73]
	v_mfma_f32_16x16x32_bf16 v[66:69], v[238:241], v[196:199], v[66:69]
	s_barrier
	s_mov_b32 m0, s98
	ds_read_b128 v[176:179], v229 offset:18432
	ds_read_b128 v[180:183], v229 offset:19456
	ds_read_b128 v[184:187], v229 offset:20480
	ds_read_b128 v[188:191], v229 offset:21504
	ds_read_b128 v[192:195], v229 offset:22528
	ds_read_b128 v[196:199], v229 offset:23552
	global_load_lds_dwordx4 v156, s[44:45]
	s_mov_b32 m0, s99
	s_add_u32 s46, s46, s95
	global_load_lds_dwordx4 v160, s[44:45]
	s_addc_u32 s47, s47, 0
	s_barrier
	s_waitcnt lgkmcnt(0)
	v_mfma_f32_16x16x32_bf16 v[62:65], v[130:133], v[242:245], v[62:65]
	v_mfma_f32_16x16x32_bf16 v[58:61], v[138:141], v[242:245], v[58:61]
	v_mfma_f32_16x16x32_bf16 v[46:49], v[130:133], v[176:179], v[46:49]
	v_mfma_f32_16x16x32_bf16 v[42:45], v[138:141], v[176:179], v[42:45]
	v_mfma_f32_16x16x32_bf16 v[30:33], v[130:133], v[184:187], v[30:33]
	v_mfma_f32_16x16x32_bf16 v[26:29], v[138:141], v[184:187], v[26:29]
	v_mfma_f32_16x16x32_bf16 v[14:17], v[130:133], v[192:195], v[14:17]
	v_mfma_f32_16x16x32_bf16 v[10:13], v[138:141], v[192:195], v[10:13]
	v_mfma_f32_16x16x32_bf16 v[62:65], v[134:137], v[246:249], v[62:65]
	v_mfma_f32_16x16x32_bf16 v[58:61], v[142:145], v[246:249], v[58:61]
	v_mfma_f32_16x16x32_bf16 v[46:49], v[134:137], v[180:183], v[46:49]
	v_mfma_f32_16x16x32_bf16 v[42:45], v[142:145], v[180:183], v[42:45]
	v_mfma_f32_16x16x32_bf16 v[30:33], v[134:137], v[188:191], v[30:33]
	v_mfma_f32_16x16x32_bf16 v[26:29], v[142:145], v[188:191], v[26:29]
	v_mfma_f32_16x16x32_bf16 v[14:17], v[134:137], v[196:199], v[14:17]
	v_mfma_f32_16x16x32_bf16 v[10:13], v[142:145], v[196:199], v[10:13]
	s_barrier
	s_add_i32 vcc_lo, s97, 0x14000
	s_add_i32 vcc_hi, s97, 0x16000
	s_mov_b32 m0, vcc_lo
	s_add_u32 s44, s44, s20
	global_load_lds_dwordx4 v158, s[46:47]
	s_mov_b32 m0, vcc_hi
	s_addc_u32 s45, s45, 0
	global_load_lds_dwordx4 v162, s[46:47]
	v_add_u32_e32 v0, 0x18000, v224
	ds_read_b128 v[130:133], v0
	ds_read_b128 v[134:137], v0 offset:1024
	ds_read_b128 v[138:141], v0 offset:2048
	ds_read_b128 v[142:145], v0 offset:3072
	ds_read_b128 v[146:149], v229 offset:32768
	ds_read_b128 v[150:153], v229 offset:33792
	s_waitcnt vmcnt(6)
	s_barrier
	v_mfma_f32_16x16x32_bf16 v[54:57], v[200:203], v[242:245], v[54:57]
	v_mfma_f32_16x16x32_bf16 v[50:53], v[234:237], v[242:245], v[50:53]
	v_mfma_f32_16x16x32_bf16 v[38:41], v[200:203], v[176:179], v[38:41]
	v_mfma_f32_16x16x32_bf16 v[34:37], v[234:237], v[176:179], v[34:37]
	v_mfma_f32_16x16x32_bf16 v[22:25], v[200:203], v[184:187], v[22:25]
	v_mfma_f32_16x16x32_bf16 v[18:21], v[234:237], v[184:187], v[18:21]
	v_mfma_f32_16x16x32_bf16 v[6:9], v[200:203], v[192:195], v[6:9]
	v_mfma_f32_16x16x32_bf16 v[2:5], v[234:237], v[192:195], v[2:5]
	v_mfma_f32_16x16x32_bf16 v[54:57], v[230:233], v[246:249], v[54:57]
	v_mfma_f32_16x16x32_bf16 v[50:53], v[238:241], v[246:249], v[50:53]
	v_mfma_f32_16x16x32_bf16 v[38:41], v[230:233], v[180:183], v[38:41]
	v_mfma_f32_16x16x32_bf16 v[34:37], v[238:241], v[180:183], v[34:37]
	v_mfma_f32_16x16x32_bf16 v[22:25], v[230:233], v[188:191], v[22:25]
	v_mfma_f32_16x16x32_bf16 v[18:21], v[238:241], v[188:191], v[18:21]
	v_mfma_f32_16x16x32_bf16 v[6:9], v[230:233], v[196:199], v[6:9]
	v_mfma_f32_16x16x32_bf16 v[2:5], v[238:241], v[196:199], v[2:5]
	s_barrier
	s_mov_b32 m0, s94
	ds_read_b128 v[176:179], v229 offset:34816
	ds_read_b128 v[180:183], v229 offset:35840
	ds_read_b128 v[184:187], v229 offset:36864
	ds_read_b128 v[188:191], v229 offset:37888
	ds_read_b128 v[192:195], v229 offset:38912
	ds_read_b128 v[196:199], v229 offset:39936
	global_load_lds_dwordx4 v156, s[44:45]
	s_mov_b32 m0, s65
	s_nop 0
	global_load_lds_dwordx4 v160, s[44:45]
	s_waitcnt lgkmcnt(6)
	s_barrier
	s_waitcnt lgkmcnt(0)
	v_mfma_f32_16x16x32_bf16 v[126:129], v[130:133], v[146:149], v[126:129]
	v_mfma_f32_16x16x32_bf16 v[122:125], v[138:141], v[146:149], v[122:125]
	v_mfma_f32_16x16x32_bf16 v[110:113], v[130:133], v[176:179], v[110:113]
	v_mfma_f32_16x16x32_bf16 v[106:109], v[138:141], v[176:179], v[106:109]
	v_mfma_f32_16x16x32_bf16 v[94:97], v[130:133], v[184:187], v[94:97]
	v_mfma_f32_16x16x32_bf16 v[90:93], v[138:141], v[184:187], v[90:93]
	v_mfma_f32_16x16x32_bf16 v[78:81], v[130:133], v[192:195], v[78:81]
	v_mfma_f32_16x16x32_bf16 v[74:77], v[138:141], v[192:195], v[74:77]
	v_mfma_f32_16x16x32_bf16 v[126:129], v[134:137], v[150:153], v[126:129]
	v_mfma_f32_16x16x32_bf16 v[122:125], v[142:145], v[150:153], v[122:125]
	v_mfma_f32_16x16x32_bf16 v[110:113], v[134:137], v[180:183], v[110:113]
	v_mfma_f32_16x16x32_bf16 v[106:109], v[142:145], v[180:183], v[106:109]
	v_mfma_f32_16x16x32_bf16 v[94:97], v[134:137], v[188:191], v[94:97]
	v_mfma_f32_16x16x32_bf16 v[90:93], v[142:145], v[188:191], v[90:93]
	v_mfma_f32_16x16x32_bf16 v[78:81], v[134:137], v[196:199], v[78:81]
	v_mfma_f32_16x16x32_bf16 v[74:77], v[142:145], v[196:199], v[74:77]
	s_barrier
	s_sub_u32 s46, s46, s95
	s_subb_u32 s47, s47, 0
	v_add_u32_e32 v0, 0x1c000, v224
	s_add_i32 vcc_lo, s97, 0x17f80
	s_add_i32 vcc_hi, s97, 0x19f80
	s_mov_b32 m0, vcc_lo
	ds_read_b128 v[200:203], v0
	ds_read_b128 v[230:233], v0 offset:1024
	ds_read_b128 v[234:237], v0 offset:2048
	ds_read_b128 v[238:241], v0 offset:3072
	ds_read_b128 v[242:245], v229 offset:49152
	ds_read_b128 v[246:249], v229 offset:50176
	global_load_lds_dwordx4 v158, s[46:47] offset:128
	s_mov_b32 m0, vcc_hi
	s_sub_u32 s44, s44, s20
	global_load_lds_dwordx4 v162, s[46:47] offset:128
	s_subb_u32 s45, s45, 0
	s_waitcnt vmcnt(6)
	s_barrier
	s_waitcnt lgkmcnt(0)
	v_mfma_f32_16x16x32_bf16 v[118:121], v[200:203], v[146:149], v[118:121]
	v_mfma_f32_16x16x32_bf16 v[114:117], v[234:237], v[146:149], v[114:117]
	v_mfma_f32_16x16x32_bf16 v[102:105], v[200:203], v[176:179], v[102:105]
	v_mfma_f32_16x16x32_bf16 v[98:101], v[234:237], v[176:179], v[98:101]
	v_mfma_f32_16x16x32_bf16 v[86:89], v[200:203], v[184:187], v[86:89]
	v_mfma_f32_16x16x32_bf16 v[82:85], v[234:237], v[184:187], v[82:85]
	v_mfma_f32_16x16x32_bf16 v[70:73], v[200:203], v[192:195], v[70:73]
	v_mfma_f32_16x16x32_bf16 v[66:69], v[234:237], v[192:195], v[66:69]
	v_mfma_f32_16x16x32_bf16 v[118:121], v[230:233], v[150:153], v[118:121]
	v_mfma_f32_16x16x32_bf16 v[114:117], v[238:241], v[150:153], v[114:117]
	v_mfma_f32_16x16x32_bf16 v[102:105], v[230:233], v[180:183], v[102:105]
	v_mfma_f32_16x16x32_bf16 v[98:101], v[238:241], v[180:183], v[98:101]
	v_mfma_f32_16x16x32_bf16 v[86:89], v[230:233], v[188:191], v[86:89]
	v_mfma_f32_16x16x32_bf16 v[82:85], v[238:241], v[188:191], v[82:85]
	v_mfma_f32_16x16x32_bf16 v[70:73], v[230:233], v[196:199], v[70:73]
	v_mfma_f32_16x16x32_bf16 v[66:69], v[238:241], v[196:199], v[66:69]
	s_barrier
	s_add_i32 m0, s87, 0xffffff80
	ds_read_b128 v[176:179], v229 offset:51200
	ds_read_b128 v[180:183], v229 offset:52224
	ds_read_b128 v[184:187], v229 offset:53248
	ds_read_b128 v[188:191], v229 offset:54272
	ds_read_b128 v[192:195], v229 offset:55296
	ds_read_b128 v[196:199], v229 offset:56320
	global_load_lds_dwordx4 v156, s[44:45] offset:128
	s_add_i32 m0, s29, 0xffffff80
	s_add_u32 s46, s46, s95
	global_load_lds_dwordx4 v160, s[44:45] offset:128
	s_addc_u32 s47, s47, 0
	s_barrier
	s_waitcnt lgkmcnt(0)
	v_mfma_f32_16x16x32_bf16 v[62:65], v[130:133], v[242:245], v[62:65]
	v_mfma_f32_16x16x32_bf16 v[58:61], v[138:141], v[242:245], v[58:61]
	v_mfma_f32_16x16x32_bf16 v[46:49], v[130:133], v[176:179], v[46:49]
	v_mfma_f32_16x16x32_bf16 v[42:45], v[138:141], v[176:179], v[42:45]
	v_mfma_f32_16x16x32_bf16 v[30:33], v[130:133], v[184:187], v[30:33]
	v_mfma_f32_16x16x32_bf16 v[26:29], v[138:141], v[184:187], v[26:29]
	v_mfma_f32_16x16x32_bf16 v[14:17], v[130:133], v[192:195], v[14:17]
	v_mfma_f32_16x16x32_bf16 v[10:13], v[138:141], v[192:195], v[10:13]
	v_mfma_f32_16x16x32_bf16 v[62:65], v[134:137], v[246:249], v[62:65]
	v_mfma_f32_16x16x32_bf16 v[58:61], v[142:145], v[246:249], v[58:61]
	v_mfma_f32_16x16x32_bf16 v[46:49], v[134:137], v[180:183], v[46:49]
	v_mfma_f32_16x16x32_bf16 v[42:45], v[142:145], v[180:183], v[42:45]
	v_mfma_f32_16x16x32_bf16 v[30:33], v[134:137], v[188:191], v[30:33]
	v_mfma_f32_16x16x32_bf16 v[26:29], v[142:145], v[188:191], v[26:29]
	v_mfma_f32_16x16x32_bf16 v[14:17], v[134:137], v[196:199], v[14:17]
	v_mfma_f32_16x16x32_bf16 v[10:13], v[142:145], v[196:199], v[10:13]
	s_barrier
	s_add_i32 vcc_lo, s97, 0x1bf80
	s_add_i32 vcc_hi, s97, 0x1df80
	s_mov_b32 m0, vcc_lo
	s_add_u32 s0, s0, 0x100
	global_load_lds_dwordx4 v158, s[46:47] offset:128
	s_mov_b32 m0, vcc_hi
	s_addc_u32 s1, s1, 0
	global_load_lds_dwordx4 v162, s[46:47] offset:128
	v_add_u32_e32 v0, 0x10000, v224
	ds_read_b128 v[130:133], v0
	ds_read_b128 v[134:137], v0 offset:1024
	ds_read_b128 v[138:141], v0 offset:2048
	ds_read_b128 v[142:145], v0 offset:3072
	ds_read_b128 v[146:149], v229
	ds_read_b128 v[150:153], v229 offset:1024
	s_add_u32 s48, s48, 0x100
	s_addc_u32 s49, s49, 0
	s_cmp_ge_i32 s71, s6
	s_cselect_b64 vcc, -1, 0
	s_mov_b32 s44, s71
	s_add_i32 s71, s44, 2
	s_add_u32 s46, s0, 0x80
	s_addc_u32 s45, s1, 0
	s_cmp_eq_u32 s43, s44
	s_cselect_b32 s44, s72, s46
	s_cselect_b32 s45, s73, s45
	s_cselect_b32 s47, s75, s49
	s_cselect_b32 s46, s74, s48
	s_waitcnt vmcnt(6)
	s_barrier
	v_mfma_f32_16x16x32_bf16 v[54:57], v[200:203], v[242:245], v[54:57]
	v_mfma_f32_16x16x32_bf16 v[50:53], v[234:237], v[242:245], v[50:53]
	v_mfma_f32_16x16x32_bf16 v[38:41], v[200:203], v[176:179], v[38:41]
	v_mfma_f32_16x16x32_bf16 v[34:37], v[234:237], v[176:179], v[34:37]
	v_mfma_f32_16x16x32_bf16 v[22:25], v[200:203], v[184:187], v[22:25]
	v_mfma_f32_16x16x32_bf16 v[18:21], v[234:237], v[184:187], v[18:21]
	v_mfma_f32_16x16x32_bf16 v[6:9], v[200:203], v[192:195], v[6:9]
	v_mfma_f32_16x16x32_bf16 v[2:5], v[234:237], v[192:195], v[2:5]
	v_mfma_f32_16x16x32_bf16 v[54:57], v[230:233], v[246:249], v[54:57]
	v_mfma_f32_16x16x32_bf16 v[50:53], v[238:241], v[246:249], v[50:53]
	v_mfma_f32_16x16x32_bf16 v[38:41], v[230:233], v[180:183], v[38:41]
	v_mfma_f32_16x16x32_bf16 v[34:37], v[238:241], v[180:183], v[34:37]
	v_mfma_f32_16x16x32_bf16 v[22:25], v[230:233], v[188:191], v[22:25]
	v_mfma_f32_16x16x32_bf16 v[18:21], v[238:241], v[188:191], v[18:21]
	v_mfma_f32_16x16x32_bf16 v[6:9], v[230:233], v[196:199], v[6:9]
	v_mfma_f32_16x16x32_bf16 v[2:5], v[238:241], v[196:199], v[2:5]
	s_barrier
	s_cbranch_vccz .LBB0_386
	s_waitcnt lgkmcnt(0)
	s_lshl_b32 s46, s77, 8
	s_cmp_lt_i32 s64, 1
	s_mov_b64 s[0:1], -1
	s_cbranch_scc1 .LBB0_403
